# silu(z) hoisted into in-proj epilogue + g1 prefetch of conv k/v section rows (L2 warm)
# speedup vs baseline: 1.0478x; 1.0478x over previous
.LBB0_302:
	s_or_b64 exec, exec, s[60:61]
	s_or_b32 s88, s1, s0
	v_or_b32_e32 v47, s88, v47
	v_mad_i64_i32 v[64:65], s[0:1], v47, s45, v[48:49]
	global_load_dwordx4 v[50:53], v[64:65], off
	v_add_u32_e32 v70, 4, v57
	v_mad_i64_i32 v[70:71], s[0:1], v70, s45, v[48:49]
	global_load_dwordx4 v[86:89], v[70:71], off
	s_mov_b32 s100, 0x2800
	s_mov_b32 s101, 0
	v_lshl_add_u64 v[146:147], v[64:65], 0, s[100:101]
	v_lshl_add_u64 v[148:149], v[70:71], 0, s[100:101]
	global_load_dwordx4 v[150:153], v[64:65], off offset:1024
	global_load_dwordx4 v[154:157], v[70:71], off offset:1024
	global_load_dwordx4 v[158:161], v[146:147], off offset:1024
	global_load_dwordx4 v[162:165], v[148:149], off offset:1024
	global_load_dwordx4 v[166:169], v[64:65], off offset:2048
	global_load_dwordx4 v[170:173], v[70:71], off offset:2048
	global_load_dwordx4 v[174:177], v[146:147], off offset:2048
	global_load_dwordx4 v[178:181], v[148:149], off offset:2048
	s_waitcnt vmcnt(8)
	v_lshlrev_b32_e32 v54, 16, v37
	v_and_b32_e32 v55, 0xffff0000, v37
	v_mad_i32_i24 v140, v46, s62, 0
	v_lshlrev_b32_e32 v46, 16, v45
	v_and_b32_e32 v47, 0xffff0000, v45
	v_lshlrev_b32_e32 v74, 16, v44
	v_and_b32_e32 v75, 0xffff0000, v44
	v_lshlrev_b32_e32 v80, 16, v39
	v_and_b32_e32 v81, 0xffff0000, v39
	v_lshlrev_b32_e32 v44, 16, v35
	v_and_b32_e32 v45, 0xffff0000, v35
	v_lshlrev_b32_e32 v84, 16, v38
	v_and_b32_e32 v85, 0xffff0000, v38
	v_lshlrev_b32_e32 v38, 16, v34
	v_and_b32_e32 v39, 0xffff0000, v34
	v_pk_fma_f32 v[34:35], v[20:21], v[54:55], 0 op_sel_hi:[1,1,0]
	v_lshlrev_b32_e32 v76, 16, v41
	v_and_b32_e32 v77, 0xffff0000, v41
	v_lshlrev_b32_e32 v78, 16, v40
	v_and_b32_e32 v79, 0xffff0000, v40
	v_lshlrev_b32_e32 v40, 16, v36
	v_and_b32_e32 v41, 0xffff0000, v36
	v_lshlrev_b32_e32 v36, 16, v43
	v_and_b32_e32 v37, 0xffff0000, v43
	v_pk_fma_f32 v[44:45], v[4:5], v[44:45], 0 op_sel_hi:[1,1,0]
	v_pk_fma_f32 v[34:35], v[24:25], v[46:47], v[34:35]
	v_pk_fma_f32 v[44:45], v[12:13], v[36:37], v[44:45]
	v_pk_fma_f32 v[92:93], v[28:29], v[76:77], v[34:35]
	v_and_b32_e32 v102, 64, v137
	v_pk_fma_f32 v[94:95], v[16:17], v[80:81], v[44:45]
	v_xor_b32_e32 v82, 1, v137
	v_add_u32_e32 v118, 64, v102
	v_cmp_lt_i32_e32 vcc, v82, v118
	v_lshlrev_b32_e32 v100, 16, v42
	v_and_b32_e32 v101, 0xffff0000, v42
	v_cndmask_b32_e32 v82, v137, v82, vcc
	v_lshlrev_b32_e32 v103, 2, v82
	v_pk_fma_f32 v[54:55], v[2:3], v[38:39], 0 op_sel_hi:[1,1,0]
	v_pk_fma_f32 v[46:47], v[20:21], v[46:47], 0 op_sel_hi:[1,1,0]
	v_pk_fma_f32 v[54:55], v[10:11], v[100:101], v[54:55]
	v_pk_fma_f32 v[46:47], v[24:25], v[76:77], v[46:47]
	v_pk_fma_f32 v[54:55], v[14:15], v[84:85], v[54:55]
	v_pk_fma_f32 v[42:43], v[18:19], v[40:41], 0 op_sel_hi:[1,1,0]
	v_pk_fma_f32 v[36:37], v[4:5], v[36:37], 0 op_sel_hi:[1,1,0]
	v_pk_fma_f32 v[42:43], v[22:23], v[74:75], v[42:43]
	v_pk_fma_f32 v[36:37], v[12:13], v[80:81], v[36:37]
	v_pk_fma_f32 v[42:43], v[26:27], v[78:79], v[42:43]
	v_add_u32_e32 v72, 5, v57
	v_mad_i64_i32 v[72:73], s[0:1], v72, s45, v[48:49]
	global_load_dwordx4 v[38:41], v[72:73], off
	v_pk_fma_f32 v[80:81], v[4:5], v[80:81], 0 op_sel_hi:[1,1,0]
	v_lshlrev_b32_e32 v90, 16, v53
	v_and_b32_e32 v91, 0xffff0000, v53
	v_lshlrev_b32_e32 v44, 16, v51
	v_and_b32_e32 v45, 0xffff0000, v51
	v_lshlrev_b32_e32 v34, 16, v50
	v_and_b32_e32 v35, 0xffff0000, v50
	v_pk_fma_f32 v[50:51], v[32:33], v[90:91], v[92:93]
	v_lshlrev_b32_e32 v82, 16, v52
	v_mul_f32_e32 v92, 0xbfb8aa3b, v50
	v_mul_f32_e32 v93, 0xbfb8aa3b, v51
	v_exp_f32_e32 v92, v92
	v_exp_f32_e32 v93, v93
	v_and_b32_e32 v83, 0xffff0000, v52
	v_pk_fma_f32 v[52:53], v[8:9], v[44:45], v[94:95]
	v_add_f32_e32 v92, 1.0, v92
	v_mul_f32_e32 v96, 0xbfb8aa3b, v52
	v_mul_f32_e32 v97, 0xbfb8aa3b, v53
	v_exp_f32_e32 v96, v96
	v_exp_f32_e32 v97, v97
	v_add_f32_e32 v93, 1.0, v93
	v_rcp_f32_e32 v92, v92
	v_rcp_f32_e32 v93, v93
	v_pk_fma_f32 v[54:55], v[6:7], v[34:35], v[54:55]
	v_add_f32_e32 v96, 1.0, v96
	v_add_f32_e32 v97, 1.0, v97
	v_mul_f32_e32 v98, 0xbfb8aa3b, v54
	v_rcp_f32_e32 v96, v96
	v_rcp_f32_e32 v97, v97
	v_pk_mul_f32 v[112:113], v[50:51], v[92:93]
	v_mul_f32_e32 v51, 0xbfb8aa3b, v55
	v_exp_f32_e32 v50, v98
	v_exp_f32_e32 v51, v51
	v_lshlrev_b32_e32 v98, 16, v89
	v_and_b32_e32 v99, 0xffff0000, v89
	v_pk_fma_f32 v[46:47], v[28:29], v[90:91], v[46:47]
	v_pk_mul_f32 v[114:115], v[52:53], v[96:97]
	v_pk_fma_f32 v[46:47], v[32:33], v[98:99], v[46:47]
	v_add_f32_e32 v50, 1.0, v50
	v_mul_f32_e32 v52, 0xbfb8aa3b, v46
	v_mul_f32_e32 v53, 0xbfb8aa3b, v47
	v_add_f32_e32 v51, 1.0, v51
	v_exp_f32_e32 v52, v52
	v_exp_f32_e32 v53, v53
	v_pk_fma_f32 v[42:43], v[30:31], v[82:83], v[42:43]
	v_rcp_f32_e32 v50, v50
	v_rcp_f32_e32 v51, v51
	v_mul_f32_e32 v94, 0xbfb8aa3b, v42
	v_mul_f32_e32 v95, 0xbfb8aa3b, v43
	v_exp_f32_e32 v94, v94
	v_exp_f32_e32 v95, v95
	v_add_f32_e32 v52, 1.0, v52
	v_add_f32_e32 v53, 1.0, v53
	v_rcp_f32_e32 v52, v52
	v_rcp_f32_e32 v53, v53
	v_pk_mul_f32 v[116:117], v[54:55], v[50:51]
	v_pk_fma_f32 v[50:51], v[18:19], v[74:75], 0 op_sel_hi:[1,1,0]
	v_add_f32_e32 v94, 1.0, v94
	v_pk_fma_f32 v[50:51], v[22:23], v[78:79], v[50:51]
	v_add_f32_e32 v95, 1.0, v95
	v_lshlrev_b32_e32 v96, 16, v88
	v_and_b32_e32 v97, 0xffff0000, v88
	v_pk_fma_f32 v[50:51], v[26:27], v[82:83], v[50:51]
	v_rcp_f32_e32 v94, v94
	v_rcp_f32_e32 v95, v95
	v_pk_fma_f32 v[50:51], v[30:31], v[96:97], v[50:51]
	v_pk_mul_f32 v[46:47], v[46:47], v[52:53]
	v_mul_f32_e32 v52, 0xbfb8aa3b, v50
	v_mul_f32_e32 v53, 0xbfb8aa3b, v51
	v_exp_f32_e32 v52, v52
	v_exp_f32_e32 v53, v53
	v_pk_mul_f32 v[42:43], v[42:43], v[94:95]
	v_lshlrev_b32_e32 v94, 16, v87
	v_and_b32_e32 v95, 0xffff0000, v87
	v_pk_fma_f32 v[36:37], v[16:17], v[44:45], v[36:37]
	v_add_f32_e32 v52, 1.0, v52
	v_pk_fma_f32 v[36:37], v[8:9], v[94:95], v[36:37]
	v_add_f32_e32 v53, 1.0, v53
	v_mul_f32_e32 v54, 0xbfb8aa3b, v36
	v_mul_f32_e32 v55, 0xbfb8aa3b, v37
	v_rcp_f32_e32 v52, v52
	v_rcp_f32_e32 v53, v53
	v_exp_f32_e32 v54, v54
	v_exp_f32_e32 v55, v55
	v_lshlrev_b32_e32 v92, 16, v86
	v_pk_mul_f32 v[50:51], v[50:51], v[52:53]
	v_add_f32_e32 v52, 1.0, v54
	v_add_f32_e32 v53, 1.0, v55
	v_pk_fma_f32 v[54:55], v[2:3], v[100:101], 0 op_sel_hi:[1,1,0]
	v_and_b32_e32 v93, 0xffff0000, v86
	v_pk_fma_f32 v[54:55], v[10:11], v[84:85], v[54:55]
	v_rcp_f32_e32 v52, v52
	v_pk_fma_f32 v[54:55], v[14:15], v[34:35], v[54:55]
	v_rcp_f32_e32 v53, v53
	v_pk_fma_f32 v[54:55], v[6:7], v[92:93], v[54:55]
	v_pk_mul_f32 v[110:111], v[116:117], v[116:117]
	v_mul_f32_e32 v86, 0xbfb8aa3b, v54
	v_mul_f32_e32 v87, 0xbfb8aa3b, v55
	v_exp_f32_e32 v86, v86
	v_exp_f32_e32 v87, v87
	v_pk_mul_f32 v[52:53], v[36:37], v[52:53]
	v_pk_mul_f32 v[108:109], v[114:115], v[114:115]
	v_add_f32_e32 v86, 1.0, v86
	v_add_f32_e32 v87, 1.0, v87
	v_rcp_f32_e32 v86, v86
	v_rcp_f32_e32 v87, v87
	v_pk_mul_f32 v[36:37], v[52:53], v[52:53]
	v_mov_b32_e32 v101, v110
	v_pk_mul_f32 v[106:107], v[42:43], v[42:43]
	v_pk_mul_f32 v[54:55], v[54:55], v[86:87]
	v_pk_mul_f32 v[88:89], v[50:51], v[50:51]
	v_pk_mul_f32 v[86:87], v[54:55], v[54:55]
	v_pk_mul_f32 v[104:105], v[112:113], v[112:113]
	v_mov_b32_e32 v100, v86
	v_mov_b32_e32 v110, v87
	v_pk_add_f32 v[86:87], v[100:101], v[110:111]
	v_mov_b32_e32 v100, v36
	v_mov_b32_e32 v101, v108
	v_pk_add_f32 v[86:87], v[100:101], v[86:87]
	v_mov_b32_e32 v108, v37
	v_pk_add_f32 v[36:37], v[108:109], v[86:87]
	v_mov_b32_e32 v86, v88
	v_mov_b32_e32 v87, v106
	v_pk_mul_f32 v[74:75], v[46:47], v[46:47]
	v_pk_add_f32 v[36:37], v[86:87], v[36:37]
	v_mov_b32_e32 v106, v89
	v_pk_add_f32 v[36:37], v[106:107], v[36:37]
	v_mov_b32_e32 v86, v74
	v_mov_b32_e32 v87, v104
	v_pk_add_f32 v[36:37], v[86:87], v[36:37]
	v_mov_b32_e32 v104, v75
	v_pk_add_f32 v[36:37], v[104:105], v[36:37]
	ds_bpermute_b32 v75, v103, v37
	ds_bpermute_b32 v74, v103, v36
	v_xor_b32_e32 v86, 2, v137
	v_cmp_lt_i32_e32 vcc, v86, v118
	v_pk_fma_f32 v[80:81], v[12:13], v[44:45], v[80:81]
	v_pk_fma_f32 v[4:5], v[4:5], v[44:45], 0 op_sel_hi:[1,1,0]
	v_cndmask_b32_e32 v86, v137, v86, vcc
	v_lshlrev_b32_e32 v104, 2, v86
	s_waitcnt lgkmcnt(0)
	v_pk_add_f32 v[36:37], v[36:37], v[74:75]
	ds_bpermute_b32 v75, v104, v37
	ds_bpermute_b32 v74, v104, v36
	v_xor_b32_e32 v86, 4, v137
	v_cmp_lt_i32_e32 vcc, v86, v118
	v_pk_fma_f32 v[80:81], v[16:17], v[94:95], v[80:81]
	v_pk_fma_f32 v[4:5], v[12:13], v[94:95], v[4:5]
	v_cndmask_b32_e32 v86, v137, v86, vcc
	v_lshlrev_b32_e32 v105, 2, v86
	s_waitcnt lgkmcnt(0)
	v_pk_add_f32 v[36:37], v[36:37], v[74:75]
	ds_bpermute_b32 v75, v105, v37
	ds_bpermute_b32 v74, v105, v36
	v_xor_b32_e32 v86, 8, v137
	v_cmp_lt_i32_e32 vcc, v86, v118
	v_lshl_add_u32 v107, v141, 1, v140
	v_mad_u32_u24 v122, v142, s64, v107
	s_waitcnt lgkmcnt(0)
	v_pk_add_f32 v[36:37], v[36:37], v[74:75]
	v_add_u32_e32 v74, 6, v57
	v_mad_i64_i32 v[74:75], s[0:1], v74, s45, v[48:49]
	global_load_dwordx4 v[108:111], v[74:75], off
	v_cndmask_b32_e32 v86, v137, v86, vcc
	v_lshlrev_b32_e32 v106, 2, v86
	ds_bpermute_b32 v87, v106, v37
	ds_bpermute_b32 v86, v106, v36
	s_waitcnt lgkmcnt(0)
	v_pk_add_f32 v[36:37], v[36:37], v[86:87]
	s_nop 0
	v_pk_add_f32 v[48:49], v[36:37], s[44:45] op_sel_hi:[1,0]
	s_waitcnt vmcnt(0)
	v_lshlrev_b32_e32 v12, 16, v109
	v_mul_f32_e32 v36, 0x4b800000, v49
	v_cmp_gt_f32_e32 vcc, s65, v49
	v_and_b32_e32 v13, 0xffff0000, v109
	s_nop 0
	v_cndmask_b32_e32 v36, v49, v36, vcc
	v_rsq_f32_e32 v37, v36
	v_mov_b32_e32 v36, 0
	v_mul_f32_e32 v49, 0x45800000, v37
	v_cndmask_b32_e32 v37, v37, v49, vcc
	v_mul_f32_e32 v88, 0x3db504f3, v37
	v_pk_mul_f32 v[86:87], v[42:43], v[88:89] op_sel_hi:[1,0]
	v_pk_fma_f32 v[42:43], v[20:21], v[76:77], 0 op_sel_hi:[1,1,0]
	v_pk_mul_f32 v[100:101], v[116:117], v[88:89] op_sel_hi:[1,0]
	v_pk_fma_f32 v[42:43], v[24:25], v[90:91], v[42:43]
	v_pk_mul_f32 v[114:115], v[114:115], v[88:89] op_sel_hi:[1,0]
	v_pk_mul_f32 v[88:89], v[112:113], v[88:89] op_sel_hi:[1,0]
	v_lshlrev_b32_e32 v112, 16, v41
	v_and_b32_e32 v113, 0xffff0000, v41
	v_pk_fma_f32 v[42:43], v[28:29], v[98:99], v[42:43]
	v_lshlrev_b32_e32 v116, 16, v40
	v_pk_fma_f32 v[76:77], v[32:33], v[112:113], v[42:43]
	v_cvt_pk_bf16_f32 v42, v100, v101
	v_mul_f32_e32 v37, 0xbfb8aa3b, v76
	v_exp_f32_e32 v37, v37
	v_mul_f32_e32 v41, 0xbfb8aa3b, v77
	v_exp_f32_e32 v41, v41
	v_and_b32_e32 v117, 0xffff0000, v40
	v_add_f32_e32 v37, 1.0, v37
	v_rcp_f32_e32 v100, v37
	v_add_f32_e32 v37, 1.0, v41
	v_pk_fma_f32 v[40:41], v[18:19], v[78:79], 0 op_sel_hi:[1,1,0]
	v_rcp_f32_e32 v101, v37
	v_pk_fma_f32 v[40:41], v[22:23], v[82:83], v[40:41]
	v_cvt_pk_bf16_f32 v43, v114, v115
	v_pk_fma_f32 v[40:41], v[26:27], v[96:97], v[40:41]
	v_lshlrev_b32_e32 v114, 16, v39
	v_pk_fma_f32 v[118:119], v[30:31], v[116:117], v[40:41]
	v_and_b32_e32 v115, 0xffff0000, v39
	v_mul_f32_e32 v40, 0xbfb8aa3b, v118
	v_exp_f32_e32 v40, v40
	v_mul_f32_e32 v41, 0xbfb8aa3b, v119
	v_exp_f32_e32 v41, v41
	v_pk_fma_f32 v[80:81], v[8:9], v[114:115], v[80:81]
	v_add_f32_e32 v37, 1.0, v40
	v_rcp_f32_e32 v120, v37
	v_add_f32_e32 v37, 1.0, v41
	v_rcp_f32_e32 v121, v37
	v_mul_f32_e32 v37, 0xbfb8aa3b, v80
	v_exp_f32_e32 v37, v37
	v_mul_f32_e32 v39, 0xbfb8aa3b, v81
	v_exp_f32_e32 v39, v39
	v_pk_mul_f32 v[40:41], v[76:77], v[100:101]
	v_add_f32_e32 v37, 1.0, v37
	v_pk_mul_f32 v[76:77], v[118:119], v[120:121]
	v_rcp_f32_e32 v118, v37
	v_add_f32_e32 v37, 1.0, v39
	v_lshlrev_b32_e32 v120, 16, v38
	v_and_b32_e32 v121, 0xffff0000, v38
	v_pk_fma_f32 v[38:39], v[2:3], v[84:85], 0 op_sel_hi:[1,1,0]
	v_pk_fma_f32 v[20:21], v[20:21], v[90:91], 0 op_sel_hi:[1,1,0]
	v_pk_fma_f32 v[38:39], v[10:11], v[34:35], v[38:39]
	v_pk_fma_f32 v[20:21], v[24:25], v[98:99], v[20:21]
	v_pk_fma_f32 v[38:39], v[14:15], v[92:93], v[38:39]
	v_pk_fma_f32 v[20:21], v[28:29], v[112:113], v[20:21]
	v_pk_fma_f32 v[84:85], v[6:7], v[120:121], v[38:39]
	v_lshlrev_b32_e32 v24, 16, v111
	v_and_b32_e32 v25, 0xffff0000, v111
	v_rcp_f32_e32 v119, v37
	v_mul_f32_e32 v37, 0xbfb8aa3b, v84
	v_pk_fma_f32 v[20:21], v[32:33], v[24:25], v[20:21]
	v_exp_f32_e32 v37, v37
	v_mul_f32_e32 v38, 0xbfb8aa3b, v85
	v_mul_f32_e32 v24, 0xbfb8aa3b, v20
	v_mul_f32_e32 v25, 0xbfb8aa3b, v21
	v_exp_f32_e32 v49, v38
	v_exp_f32_e32 v24, v24
	v_exp_f32_e32 v25, v25
	v_pk_fma_f32 v[2:3], v[2:3], v[34:35], 0 op_sel_hi:[1,1,0]
	v_add_f32_e32 v37, 1.0, v37
	v_pk_fma_f32 v[2:3], v[10:11], v[92:93], v[2:3]
	v_lshlrev_b32_e32 v10, 16, v108
	v_pk_fma_f32 v[2:3], v[14:15], v[120:121], v[2:3]
	v_and_b32_e32 v11, 0xffff0000, v108
	v_pk_mul_f32 v[38:39], v[80:81], v[118:119]
	v_rcp_f32_e32 v80, v37
	v_add_f32_e32 v37, 1.0, v49
	v_add_f32_e32 v24, 1.0, v24
	v_add_f32_e32 v25, 1.0, v25
	v_pk_fma_f32 v[4:5], v[16:17], v[114:115], v[4:5]
	v_pk_fma_f32 v[2:3], v[6:7], v[10:11], v[2:3]
	v_rcp_f32_e32 v81, v37
	v_rcp_f32_e32 v24, v24
	v_rcp_f32_e32 v25, v25
	v_pk_fma_f32 v[4:5], v[8:9], v[12:13], v[4:5]
	v_mul_f32_e32 v6, 0xbfb8aa3b, v2
	v_mul_f32_e32 v7, 0xbfb8aa3b, v3
	v_mul_f32_e32 v8, 0xbfb8aa3b, v4
	v_mul_f32_e32 v9, 0xbfb8aa3b, v5
	v_exp_f32_e32 v6, v6
	v_exp_f32_e32 v7, v7
	v_pk_fma_f32 v[18:19], v[18:19], v[82:83], 0 op_sel_hi:[1,1,0]
	v_exp_f32_e32 v8, v8
	v_exp_f32_e32 v9, v9
	v_pk_fma_f32 v[18:19], v[22:23], v[96:97], v[18:19]
	v_pk_mul_f32 v[84:85], v[84:85], v[80:81]
	v_pk_mul_f32 v[80:81], v[20:21], v[24:25]
	v_pk_fma_f32 v[18:19], v[26:27], v[116:117], v[18:19]
	v_lshlrev_b32_e32 v20, 16, v110
	v_and_b32_e32 v21, 0xffff0000, v110
	v_pk_fma_f32 v[18:19], v[30:31], v[20:21], v[18:19]
	v_add_f32_e32 v6, 1.0, v6
	v_add_f32_e32 v7, 1.0, v7
	v_mul_f32_e32 v20, 0xbfb8aa3b, v18
	v_mul_f32_e32 v21, 0xbfb8aa3b, v19
	v_add_f32_e32 v8, 1.0, v8
	v_add_f32_e32 v9, 1.0, v9
	v_rcp_f32_e32 v6, v6
	v_rcp_f32_e32 v7, v7
	v_exp_f32_e32 v20, v20
	v_exp_f32_e32 v21, v21
	v_rcp_f32_e32 v8, v8
	v_rcp_f32_e32 v9, v9
	v_pk_mul_f32 v[2:3], v[2:3], v[6:7]
	v_pk_mul_f32 v[32:33], v[84:85], v[84:85]
	v_add_f32_e32 v20, 1.0, v20
	v_add_f32_e32 v21, 1.0, v21
	v_pk_mul_f32 v[92:93], v[4:5], v[8:9]
	v_pk_mul_f32 v[6:7], v[2:3], v[2:3]
	v_pk_mul_f32 v[28:29], v[38:39], v[38:39]
	v_rcp_f32_e32 v20, v20
	v_rcp_f32_e32 v21, v21
	v_pk_mul_f32 v[4:5], v[92:93], v[92:93]
	v_mov_b32_e32 v8, v6
	v_mov_b32_e32 v9, v32
	v_mov_b32_e32 v32, v7
	v_pk_add_f32 v[6:7], v[8:9], v[32:33]
	v_mov_b32_e32 v8, v4
	v_mov_b32_e32 v9, v28
	v_pk_add_f32 v[6:7], v[8:9], v[6:7]
	v_add_co_u32_e32 v8, vcc, 0x2000, v66
	v_mov_b32_e32 v28, v5
	v_lshl_add_u64 v[12:13], v[66:67], 0, s[46:47]
	v_addc_co_u32_e32 v9, vcc, 0, v67, vcc
	v_pk_mul_f32 v[90:91], v[18:19], v[20:21]
	v_pk_add_f32 v[94:95], v[28:29], v[6:7]
	global_load_dwordx4 v[20:23], v[66:67], off offset:2064
	global_load_dwordx4 v[4:7], v[66:67], off offset:2048
	s_nop 0
	global_load_dwordx4 v[8:11], v[8:9], off
	s_nop 0
	global_load_dwordx4 v[24:27], v[12:13], off offset:16
	v_add_co_u32_e32 v12, vcc, 0x3000, v66
	v_lshl_add_u64 v[16:17], v[66:67], 0, s[48:49]
	s_nop 0
	v_addc_co_u32_e32 v13, vcc, 0, v67, vcc
	global_load_dwordx4 v[12:15], v[12:13], off offset:2048
	s_nop 0
	global_load_dwordx4 v[28:31], v[16:17], off offset:16
	v_add_co_u32_e32 v16, vcc, 0x5000, v66
	v_lshl_add_u64 v[32:33], v[66:67], 0, s[50:51]
	s_nop 0
	v_addc_co_u32_e32 v17, vcc, 0, v67, vcc
	global_load_dwordx4 v[16:19], v[16:17], off
	s_nop 0
	global_load_dwordx4 v[32:35], v[32:33], off offset:16
	v_pk_mul_f32 v[100:101], v[76:77], v[76:77]
	v_pk_mul_f32 v[44:45], v[90:91], v[90:91]
	v_mov_b32_e32 v97, v100
	v_mov_b32_e32 v96, v44
	v_pk_mul_f32 v[78:79], v[40:41], v[40:41]
	v_pk_mul_f32 v[82:83], v[80:81], v[80:81]
	v_pk_add_f32 v[94:95], v[96:97], v[94:95]
	v_mov_b32_e32 v100, v45
	v_pk_add_f32 v[44:45], v[100:101], v[94:95]
	v_mov_b32_e32 v94, v82
	v_mov_b32_e32 v95, v78
	v_pk_add_f32 v[44:45], v[94:95], v[44:45]
	v_mov_b32_e32 v78, v83
	v_pk_add_f32 v[44:45], v[78:79], v[44:45]
	ds_bpermute_b32 v79, v103, v45
	ds_bpermute_b32 v78, v103, v44
	v_mul_f32_e32 v37, 0x4b800000, v48
	v_cmp_gt_f32_e32 vcc, s65, v48
	s_nop 1
	v_cndmask_b32_e32 v37, v48, v37, vcc
	s_waitcnt lgkmcnt(0)
	v_pk_add_f32 v[48:49], v[44:45], v[78:79]
	ds_bpermute_b32 v79, v104, v49
	ds_bpermute_b32 v78, v104, v48
	v_cvt_pk_bf16_f32 v44, v86, v87
	v_cvt_pk_bf16_f32 v45, v88, v89
	ds_write_b128 v122, v[42:45] offset:17408
	v_rsq_f32_e32 v37, v37
	s_waitcnt lgkmcnt(1)
	v_pk_add_f32 v[42:43], v[48:49], v[78:79]
	ds_bpermute_b32 v45, v105, v43
	ds_bpermute_b32 v44, v105, v42
	v_mul_f32_e32 v82, 0x45800000, v37
	v_cndmask_b32_e32 v37, v37, v82, vcc
	v_mul_f32_e32 v48, 0x3db504f3, v37
	v_pk_mul_f32 v[54:55], v[54:55], v[48:49] op_sel_hi:[1,0]
	s_waitcnt lgkmcnt(0)
	v_pk_add_f32 v[44:45], v[42:43], v[44:45]
	ds_bpermute_b32 v79, v106, v45
	ds_bpermute_b32 v78, v106, v44
	v_pk_mul_f32 v[52:53], v[52:53], v[48:49] op_sel_hi:[1,0]
	v_pk_mul_f32 v[50:51], v[50:51], v[48:49] op_sel_hi:[1,0]
	v_pk_mul_f32 v[46:47], v[46:47], v[48:49] op_sel_hi:[1,0]
	v_cvt_pk_bf16_f32 v42, v54, v55
	s_waitcnt lgkmcnt(0)
	v_pk_add_f32 v[44:45], v[44:45], v[78:79]
	v_cvt_pk_bf16_f32 v43, v52, v53
	v_pk_add_f32 v[48:49], v[44:45], s[44:45] op_sel_hi:[1,0]
	v_cvt_pk_bf16_f32 v44, v50, v51
	v_mul_f32_e32 v37, 0x4b800000, v49
	v_cmp_gt_f32_e32 vcc, s65, v49
	v_cvt_pk_bf16_f32 v45, v46, v47
	ds_write_b128 v122, v[42:45] offset:17680
	v_cndmask_b32_e32 v37, v49, v37, vcc
	v_rsq_f32_e32 v37, v37
	v_mov_b32_e32 v49, 0
	v_mul_f32_e32 v42, 0x45800000, v37
	v_cndmask_b32_e32 v37, v37, v42, vcc
	v_mul_f32_e32 v42, 0x3db504f3, v37
	v_mul_f32_e32 v37, 0x4b800000, v48
	v_cmp_gt_f32_e32 vcc, s65, v48
	v_pk_mul_f32 v[44:45], v[84:85], v[42:43] op_sel_hi:[1,0]
	v_pk_mul_f32 v[46:47], v[38:39], v[42:43] op_sel_hi:[1,0]
	v_cndmask_b32_e32 v37, v48, v37, vcc
	v_rsq_f32_e32 v37, v37
	v_pk_mul_f32 v[50:51], v[76:77], v[42:43] op_sel_hi:[1,0]
	v_pk_mul_f32 v[42:43], v[40:41], v[42:43] op_sel_hi:[1,0]
	v_cvt_pk_bf16_f32 v38, v44, v45
	v_cvt_pk_bf16_f32 v39, v46, v47
	v_cvt_pk_bf16_f32 v40, v50, v51
	v_cvt_pk_bf16_f32 v41, v42, v43
	ds_write_b128 v122, v[38:41] offset:17952
	v_mul_f32_e32 v38, 0x45800000, v37
	v_cndmask_b32_e32 v37, v37, v38, vcc
	v_mul_f32_e32 v38, 0x3db504f3, v37
	v_pk_mul_f32 v[2:3], v[2:3], v[38:39] op_sel_hi:[1,0]
	v_pk_mul_f32 v[40:41], v[92:93], v[38:39] op_sel_hi:[1,0]
	v_pk_mul_f32 v[42:43], v[90:91], v[38:39] op_sel_hi:[1,0]
	v_pk_mul_f32 v[44:45], v[80:81], v[38:39] op_sel_hi:[1,0]
	v_cvt_pk_bf16_f32 v38, v2, v3
	v_cvt_pk_bf16_f32 v39, v40, v41
	v_cvt_pk_bf16_f32 v40, v42, v43
	v_cvt_pk_bf16_f32 v41, v44, v45
	ds_write_b128 v122, v[38:41] offset:18224
	v_add_u32_e32 v40, 0x200, v56
	v_ashrrev_i32_e32 v41, 31, v40
	v_mov_b32_e32 v48, 0
	v_mov_b32_e32 v50, 0
	v_mov_b32_e32 v51, 0
	s_and_saveexec_b64 s[60:61], s[2:3]
	s_cbranch_execz .LBB0_304
	v_mov_b64_e32 v[2:3], s[8:9]
	v_mad_i64_i32 v[2:3], s[0:1], v57, s45, v[2:3]
	v_lshl_add_u64 v[2:3], v[40:41], 1, v[2:3]
	global_load_dwordx4 v[48:51], v[2:3], off

	.amdhsa_kernel _Z10hymba_mega6Params
		.amdhsa_group_segment_fixed_size 0
		.amdhsa_private_segment_fixed_size 0
		.amdhsa_kernarg_size 424
		.amdhsa_user_sgpr_count 2
		.amdhsa_user_sgpr_dispatch_ptr 0
		.amdhsa_user_sgpr_queue_ptr 0
		.amdhsa_user_sgpr_kernarg_segment_ptr 1
		.amdhsa_user_sgpr_dispatch_id 0
		.amdhsa_user_sgpr_kernarg_preload_length 0
		.amdhsa_user_sgpr_kernarg_preload_offset 0
		.amdhsa_user_sgpr_private_segment_size 0
		.amdhsa_uses_dynamic_stack 0
		.amdhsa_enable_private_segment 0
		.amdhsa_system_sgpr_workgroup_id_x 1
		.amdhsa_system_sgpr_workgroup_id_y 0
		.amdhsa_system_sgpr_workgroup_id_z 0
		.amdhsa_system_sgpr_workgroup_info 0
		.amdhsa_system_vgpr_workitem_id 2
		.amdhsa_next_free_vgpr 247
		.amdhsa_next_free_sgpr 102
		.amdhsa_accum_offset 248
		.amdhsa_reserve_vcc 1
		.amdhsa_float_round_mode_32 0
		.amdhsa_float_round_mode_16_64 0
		.amdhsa_float_denorm_mode_32 3
		.amdhsa_float_denorm_mode_16_64 3
		.amdhsa_dx10_clamp 1
		.amdhsa_ieee_mode 1
		.amdhsa_fp16_overflow 0
		.amdhsa_tg_split 0
		.amdhsa_exception_fp_ieee_invalid_op 0
		.amdhsa_exception_fp_denorm_src 0
		.amdhsa_exception_fp_ieee_div_zero 0
		.amdhsa_exception_fp_ieee_overflow 0
		.amdhsa_exception_fp_ieee_underflow 0
		.amdhsa_exception_fp_ieee_inexact 0
		.amdhsa_exception_int_div_zero 0
	.end_amdhsa_kernel

amdhsa.kernels:
  - .agpr_count:     0
    .args:
      - .offset:         0
        .size:           168
        .value_kind:     by_value
      - .offset:         168
        .size:           4
        .value_kind:     hidden_block_count_x
      - .offset:         172
        .size:           4
        .value_kind:     hidden_block_count_y
      - .offset:         176
        .size:           4
        .value_kind:     hidden_block_count_z
      - .offset:         180
        .size:           2
        .value_kind:     hidden_group_size_x
      - .offset:         182
        .size:           2
        .value_kind:     hidden_group_size_y
      - .offset:         184
        .size:           2
        .value_kind:     hidden_group_size_z
      - .offset:         186
        .size:           2
        .value_kind:     hidden_remainder_x
      - .offset:         188
        .size:           2
        .value_kind:     hidden_remainder_y
      - .offset:         190
        .size:           2
        .value_kind:     hidden_remainder_z
      - .offset:         208
        .size:           8
        .value_kind:     hidden_global_offset_x
      - .offset:         216
        .size:           8
        .value_kind:     hidden_global_offset_y
      - .offset:         224
        .size:           8
        .value_kind:     hidden_global_offset_z
      - .offset:         232
        .size:           2
        .value_kind:     hidden_grid_dims
      - .offset:         256
        .size:           8
        .value_kind:     hidden_multigrid_sync_arg
      - .offset:         288
        .size:           4
        .value_kind:     hidden_dynamic_lds_size
    .group_segment_fixed_size: 0
    .kernarg_segment_align: 8
    .kernarg_segment_size: 424
    .language:       OpenCL C
    .language_version:
      - 2
      - 0
    .max_flat_workgroup_size: 512
    .name:           _Z10hymba_mega6Params
    .private_segment_fixed_size: 0
    .sgpr_count:     108
    .sgpr_spill_count: 3
    .symbol:         _Z10hymba_mega6Params.kd
    .uniform_work_group_size: 1
    .uses_dynamic_stack: false
    .vgpr_count:     247
    .vgpr_spill_count: 0
    .wavefront_size: 64
